# diff loop: dropped self-max canonicalisation of the two cross-half row-max values
# speedup vs baseline: 1.0079x; 1.0015x over previous
.LBB0_477:
	s_lshl_b32 s22, s22, 1
	v_add_u32_e32 v212, s22, v245
	ds_read_b64_tr_b16 v[208:209], v212 offset:24576
	ds_read_b64_tr_b16 v[210:211], v212 offset:25088
	v_mfma_f32_32x32x16_bf16 v[128:143], v[204:207], v[172:175], v[64:79]
	v_add_f32_e32 v112, v96, v97
	v_add_f32_e32 v112, v98, v112
	v_add_f32_e32 v112, v99, v112
	v_add_f32_e32 v112, v100, v112
	v_add_f32_e32 v112, v101, v112
	v_cvt_pk_bf16_f32 v156, v96, v97
	v_cvt_pk_bf16_f32 v157, v98, v99
	ds_read_b64_tr_b16 v[204:205], v212 offset:28672
	ds_read_b64_tr_b16 v[206:207], v212 offset:29184
	v_add_f32_e32 v96, v102, v112
	v_mfma_f32_32x32x16_bf16 v[112:127], v[196:199], v[172:175], v[64:79]
	v_add_f32_e32 v96, v103, v96
	v_add_f32_e32 v96, v104, v96
	v_add_f32_e32 v96, v105, v96
	v_cvt_pk_bf16_f32 v158, v100, v101
	v_cvt_pk_bf16_f32 v159, v102, v103
	ds_read_b64_tr_b16 v[100:101], v212 offset:25600
	ds_read_b64_tr_b16 v[102:103], v212 offset:26112
	v_mfma_f32_32x32x16_bf16 v[128:143], v[200:203], v[168:171], v[128:143]
	v_add_f32_e32 v96, v106, v96
	v_add_f32_e32 v96, v107, v96
	v_add_f32_e32 v96, v108, v96
	v_add_f32_e32 v144, v109, v96
	v_cvt_pk_bf16_f32 v152, v104, v105
	v_cvt_pk_bf16_f32 v153, v106, v107
	ds_read_b64_tr_b16 v[96:97], v212 offset:29696
	ds_read_b64_tr_b16 v[98:99], v212 offset:30208
	v_mfma_f32_32x32x16_bf16 v[112:127], v[192:195], v[168:171], v[112:127]
	v_add_f32_e32 v104, v110, v144
	v_add_f32_e32 v104, v111, v104
	v_add_f32_e32 v104, v80, v104
	v_add_f32_e32 v104, v81, v104
	v_cvt_pk_bf16_f32 v154, v108, v109
	v_cvt_pk_bf16_f32 v155, v110, v111
	ds_read_b64_tr_b16 v[108:109], v212 offset:26624
	ds_read_b64_tr_b16 v[110:111], v212 offset:27136
	v_mfma_f32_32x32x16_bf16 v[128:143], v[188:191], v[164:167], v[128:143]
	v_add_f32_e32 v104, v82, v104
	v_add_f32_e32 v104, v83, v104
	v_add_f32_e32 v104, v84, v104
	v_add_f32_e32 v144, v85, v104
	v_cvt_pk_bf16_f32 v148, v80, v81
	v_cvt_pk_bf16_f32 v149, v82, v83
	ds_read_b64_tr_b16 v[104:105], v212 offset:30720
	ds_read_b64_tr_b16 v[106:107], v212 offset:31232
	v_mfma_f32_32x32x16_bf16 v[112:127], v[184:187], v[164:167], v[112:127]
	v_add_f32_e32 v80, v86, v144
	v_add_f32_e32 v80, v87, v80
	v_add_f32_e32 v80, v88, v80
	v_add_f32_e32 v80, v89, v80
	v_cvt_pk_bf16_f32 v150, v84, v85
	v_cvt_pk_bf16_f32 v151, v86, v87
	ds_read_b64_tr_b16 v[84:85], v212 offset:27648
	ds_read_b64_tr_b16 v[86:87], v212 offset:28160
	v_mfma_f32_32x32x16_bf16 v[128:143], v[180:183], v[160:163], v[128:143]
	v_add_f32_e32 v80, v90, v80
	v_add_f32_e32 v80, v91, v80
	v_add_f32_e32 v80, v92, v80
	v_add_f32_e32 v80, v93, v80
	v_cvt_pk_bf16_f32 v144, v88, v89
	v_cvt_pk_bf16_f32 v145, v90, v91
	ds_read_b64_tr_b16 v[88:89], v212 offset:31744
	ds_read_b64_tr_b16 v[90:91], v212 offset:32256
	v_mfma_f32_32x32x16_bf16 v[112:127], v[176:179], v[160:163], v[112:127]
	v_add_f32_e32 v80, v94, v80
	v_add_f32_e32 v80, v95, v80
	v_cvt_pk_bf16_f32 v146, v92, v93
	v_cvt_pk_bf16_f32 v147, v94, v95
	s_waitcnt lgkmcnt(14)
	v_mfma_f32_32x32x16_bf16 v[0:15], v[156:159], v[208:211], v[0:15]
	v_max_f32_e32 v81, v129, v129
	v_max_f32_e32 v82, v128, v128
	v_max_f32_e32 v81, v82, v81
	s_nop 3
	v_max3_f32 v82, v130, v131, v113
	v_max3_f32 v81, v81, v112, v114
	v_max3_f32 v81, v81, v115, v132
	v_max3_f32 v82, v82, v134, v135
	s_waitcnt lgkmcnt(12)
	v_mfma_f32_32x32x16_bf16 v[48:63], v[156:159], v[204:207], v[48:63]
	s_add_u32 s37, s16, s24
	v_max3_f32 v81, v81, v133, v116
	v_max3_f32 v82, v82, v118, v119
	s_addc_u32 s39, s17, s19
	v_max3_f32 v81, v81, v117, v136
	v_max3_f32 v82, v82, v138, v139
	s_add_u32 s22, s37, 0x9b80800
	v_max3_f32 v81, v81, v137, v120
	v_max3_f32 v82, v82, v122, v123
	s_addc_u32 s23, s39, 0
	s_add_i32 s34, s33, s28
	s_mov_b32 m0, s34
	s_nop 0
	global_load_lds_dwordx4 v241, s[22:23]
	v_max3_f32 v81, v81, v121, v140
	v_max3_f32 v82, v82, v142, v143
	s_add_u32 s35, s20, s24
	v_max3_f32 v81, v81, v141, v124
	v_max3_f32 v82, v82, v126, v127
	s_addc_u32 s36, s21, s19
	v_add_f32_e32 v251, v251, v80
	v_max3_f32 v80, v81, v125, v82
	s_add_u32 s22, s35, 0x9ac1000
	v_mov_b32_e32 v81, v80
	s_addc_u32 s23, s36, 0
	s_lshl_b32 s34, s31, 1
	v_permlane32_swap_b32_e32 v80, v81
	s_add_i32 s34, s34, s29
	s_mov_b32 m0, s34
	s_nop 0
	global_load_lds_dwordx4 v242, s[22:23]
	s_add_u32 s22, s35, 0x9ac1080
	v_max_f32_e32 v80, v80, v81
	s_addc_u32 s23, s36, 0
	s_addk_i32 s34, 0x2000
	s_mov_b32 m0, s34
	s_nop 0
	global_load_lds_dwordx4 v242, s[22:23]
	v_cmp_lt_f32_e32 vcc, s25, v80
	s_cmp_lg_u64 vcc, 0
	s_cselect_b64 s[22:23], -1, 0
	s_cbranch_vccnz .LBB0_485

.LBB0_480:
	s_add_i32 s22, s31, 0x2000
	s_cmpk_lg_i32 s31, 0x4000
	s_cselect_b32 s34, s22, 0
	s_lshl_b32 s22, s33, 1
	v_add_u32_e32 v236, s22, v245
	ds_read_b64_tr_b16 v[212:213], v236 offset:24576
	ds_read_b64_tr_b16 v[214:215], v236 offset:25088
	v_mfma_f32_32x32x16_bf16 v[96:111], v[80:83], v[172:175], v[64:79]
	v_add_f32_e32 v84, v128, v129
	v_add_f32_e32 v84, v130, v84
	v_add_f32_e32 v84, v131, v84
	v_add_f32_e32 v84, v132, v84
	v_add_f32_e32 v84, v133, v84
	v_cvt_pk_bf16_f32 v156, v128, v129
	v_cvt_pk_bf16_f32 v157, v130, v131
	ds_read_b64_tr_b16 v[204:205], v236 offset:28672
	ds_read_b64_tr_b16 v[206:207], v236 offset:29184
	v_add_f32_e32 v80, v134, v84
	v_add_f32_e32 v80, v135, v80
	v_add_f32_e32 v80, v136, v80
	v_add_f32_e32 v128, v137, v80
	v_mfma_f32_32x32x16_bf16 v[80:95], v[196:199], v[172:175], v[64:79]
	v_cvt_pk_bf16_f32 v158, v132, v133
	v_cvt_pk_bf16_f32 v159, v134, v135
	ds_read_b64_tr_b16 v[208:209], v236 offset:25600
	ds_read_b64_tr_b16 v[210:211], v236 offset:26112
	v_mfma_f32_32x32x16_bf16 v[96:111], v[200:203], v[168:171], v[96:111]
	v_add_f32_e32 v128, v138, v128
	v_add_f32_e32 v128, v139, v128
	v_add_f32_e32 v128, v140, v128
	v_add_f32_e32 v128, v141, v128
	v_cvt_pk_bf16_f32 v152, v136, v137
	v_cvt_pk_bf16_f32 v153, v138, v139
	ds_read_b64_tr_b16 v[132:133], v236 offset:29696
	ds_read_b64_tr_b16 v[134:135], v236 offset:30208
	v_mfma_f32_32x32x16_bf16 v[80:95], v[192:195], v[168:171], v[80:95]
	v_add_f32_e32 v128, v142, v128
	v_add_f32_e32 v128, v143, v128
	v_add_f32_e32 v128, v112, v128
	v_add_f32_e32 v136, v113, v128
	v_cvt_pk_bf16_f32 v154, v140, v141
	v_cvt_pk_bf16_f32 v155, v142, v143
	ds_read_b64_tr_b16 v[128:129], v236 offset:26624
	ds_read_b64_tr_b16 v[130:131], v236 offset:27136
	v_mfma_f32_32x32x16_bf16 v[96:111], v[188:191], v[164:167], v[96:111]
	v_add_f32_e32 v136, v114, v136
	v_add_f32_e32 v136, v115, v136
	v_add_f32_e32 v136, v116, v136
	v_add_f32_e32 v136, v117, v136
	v_cvt_pk_bf16_f32 v148, v112, v113
	v_cvt_pk_bf16_f32 v149, v114, v115
	ds_read_b64_tr_b16 v[112:113], v236 offset:30720
	ds_read_b64_tr_b16 v[114:115], v236 offset:31232
	v_mfma_f32_32x32x16_bf16 v[80:95], v[184:187], v[164:167], v[80:95]
	v_add_f32_e32 v136, v118, v136
	v_add_f32_e32 v136, v119, v136
	v_add_f32_e32 v136, v120, v136
	v_add_f32_e32 v136, v121, v136
	v_cvt_pk_bf16_f32 v150, v116, v117
	v_cvt_pk_bf16_f32 v151, v118, v119
	ds_read_b64_tr_b16 v[116:117], v236 offset:27648
	ds_read_b64_tr_b16 v[118:119], v236 offset:28160
	v_mfma_f32_32x32x16_bf16 v[96:111], v[180:183], v[160:163], v[96:111]
	v_add_f32_e32 v136, v122, v136
	v_add_f32_e32 v136, v123, v136
	v_add_f32_e32 v136, v124, v136
	v_add_f32_e32 v136, v125, v136
	v_cvt_pk_bf16_f32 v144, v120, v121
	v_cvt_pk_bf16_f32 v145, v122, v123
	ds_read_b64_tr_b16 v[120:121], v236 offset:31744
	ds_read_b64_tr_b16 v[122:123], v236 offset:32256
	v_mfma_f32_32x32x16_bf16 v[80:95], v[176:179], v[160:163], v[80:95]
	v_add_f32_e32 v136, v126, v136
	v_add_f32_e32 v136, v127, v136
	v_cvt_pk_bf16_f32 v146, v124, v125
	v_cvt_pk_bf16_f32 v147, v126, v127
	s_waitcnt lgkmcnt(14)
	v_mfma_f32_32x32x16_bf16 v[0:15], v[156:159], v[212:215], v[0:15]
	v_max_f32_e32 v124, v97, v97
	v_max_f32_e32 v125, v96, v96
	v_max_f32_e32 v124, v125, v124
	s_nop 3
	v_max3_f32 v125, v98, v99, v81
	v_max3_f32 v124, v124, v80, v82
	v_max3_f32 v124, v124, v83, v100
	v_max3_f32 v125, v125, v102, v103
	s_waitcnt lgkmcnt(12)
	v_mfma_f32_32x32x16_bf16 v[48:63], v[156:159], v[204:207], v[48:63]
	v_max3_f32 v124, v124, v101, v84
	v_max3_f32 v125, v125, v86, v87
	v_max3_f32 v124, v124, v85, v104
	v_max3_f32 v125, v125, v106, v107
	v_max3_f32 v124, v124, v105, v88
	v_max3_f32 v125, v125, v90, v91
	v_max3_f32 v124, v124, v89, v108
	v_max3_f32 v125, v125, v110, v111
	s_add_u32 s22, s37, 0x9be0800
	v_max3_f32 v124, v124, v109, v92
	v_max3_f32 v125, v125, v94, v95
	s_addc_u32 s23, s39, 0
	s_add_i32 s33, s31, s28
	v_max3_f32 v124, v124, v93, v125
	s_mov_b32 m0, s33
	s_nop 0
	global_load_lds_dwordx4 v241, s[22:23]
	s_add_u32 s22, s35, 0x9b21000
	v_mov_b32_e32 v125, v124
	s_addc_u32 s23, s36, 0
	s_lshl_b32 s33, s34, 1
	v_permlane32_swap_b32_e32 v124, v125
	s_add_i32 s33, s33, s29
	s_mov_b32 m0, s33
	s_nop 0
	global_load_lds_dwordx4 v242, s[22:23]
	s_add_u32 s22, s35, 0x9b21080
	v_max_f32_e32 v124, v124, v125
	s_addc_u32 s23, s36, 0
	s_addk_i32 s33, 0x2000
	s_mov_b32 m0, s33
	s_nop 0
	global_load_lds_dwordx4 v242, s[22:23]
	v_cmp_lt_f32_e32 vcc, s25, v124
	s_cmp_lg_u64 vcc, 0
	v_add_f32_e32 v251, v251, v136
	s_cselect_b64 s[22:23], -1, 0
	s_cbranch_vccnz .LBB0_488
